# GEMM2 tile reservation overlapped with gate loads
# baseline (speedup 1.0000x reference)
.LBB0_608:
	v_mov_b32_e32 v194, v230
	s_mov_b32 s15, s91
	s_ashr_i32 s5, s15, 2
	s_lshl_b32 s4, s22, 8
	s_andn2_b32 s5, s5, 63
	s_and_b32 s4, s4, 0x1f00
	v_and_or_b32 v130, v194, 15, s5
	v_add_u32_e32 v228, s4, v130
	s_lshl_b32 s4, s23, 8
	s_lshr_b32 s5, s15, 1
	s_and_b32 s4, s4, 0x300
	s_and_b32 s5, s5, 0x60
	v_ashrrev_i32_e32 v130, 1, v194
	v_and_b32_e32 v130, -8, v130
	s_or_b32 s4, s5, s4
	v_add_u32_e32 v130, s4, v130
	s_lshl_b32 s4, s22, 5
	s_and_b32 s4, s4, 0xfffffc00
	s_mov_b32 s21, s71
	s_ashr_i32 s5, s4, 31
	s_mov_b32 s20, 0
	s_xor_b64 s[0:1], s[20:21], s[62:63]
	s_lshl_b64 s[4:5], s[4:5], 1
	s_add_u32 s0, s0, s4
	s_addc_u32 s1, s1, s5
	s_add_u32 s0, s0, 0xbe3e000
	s_addc_u32 s1, s1, 0
	v_ashrrev_i32_e32 v131, 31, v130
	v_mov_b64_e32 v[132:133], s[0:1]
	s_movk_i32 s4, 0x1800
	v_mad_i64_i32 v[134:135], s[0:1], v228, s4, v[132:133]
	v_lshlrev_b64 v[212:213], 1, v[130:131]
	v_lshl_add_u64 v[130:131], v[134:135], 0, v[212:213]
	v_or_b32_e32 v226, 16, v228
	flat_load_dwordx4 v[190:193], v[130:131]
	flat_load_dwordx4 v[186:189], v[130:131] offset:256
	v_mad_i64_i32 v[130:131], s[0:1], v226, s4, v[132:133]
	v_lshl_add_u64 v[130:131], v[130:131], 0, v[212:213]
	v_or_b32_e32 v224, 32, v228
	flat_load_dwordx4 v[182:185], v[130:131]
	flat_load_dwordx4 v[178:181], v[130:131] offset:256
	v_mad_i64_i32 v[130:131], s[0:1], v224, s4, v[132:133]
	v_lshl_add_u64 v[130:131], v[130:131], 0, v[212:213]
	v_or_b32_e32 v222, 48, v228
	flat_load_dwordx4 v[174:177], v[130:131]
	flat_load_dwordx4 v[170:173], v[130:131] offset:256
	v_mad_i64_i32 v[130:131], s[0:1], v222, s4, v[132:133]
	v_lshl_add_u64 v[130:131], v[130:131], 0, v[212:213]
	v_add_u32_e32 v220, 0x80, v228
	flat_load_dwordx4 v[166:169], v[130:131]
	flat_load_dwordx4 v[162:165], v[130:131] offset:256
	v_mad_i64_i32 v[130:131], s[0:1], v220, s4, v[132:133]
	v_lshl_add_u64 v[130:131], v[130:131], 0, v[212:213]
	v_add_u32_e32 v218, 0x90, v228
	flat_load_dwordx4 v[158:161], v[130:131]
	flat_load_dwordx4 v[154:157], v[130:131] offset:256
	v_mad_i64_i32 v[130:131], s[0:1], v218, s4, v[132:133]
	v_lshl_add_u64 v[130:131], v[130:131], 0, v[212:213]
	v_add_u32_e32 v216, 0xa0, v228
	flat_load_dwordx4 v[150:153], v[130:131]
	flat_load_dwordx4 v[146:149], v[130:131] offset:256
	v_mad_i64_i32 v[130:131], s[0:1], v216, s4, v[132:133]
	v_lshl_add_u64 v[130:131], v[130:131], 0, v[212:213]
	v_add_u32_e32 v214, 0xb0, v228
	flat_load_dwordx4 v[142:145], v[130:131]
	flat_load_dwordx4 v[138:141], v[130:131] offset:256
	v_mad_i64_i32 v[130:131], s[0:1], v214, s4, v[132:133]
	v_lshl_add_u64 v[130:131], v[130:131], 0, v[212:213]
	flat_load_dwordx4 v[134:137], v[130:131]
	s_nop 0
	flat_load_dwordx4 v[130:133], v[130:131] offset:256
	s_mov_b32 s20, 0
	s_xor_b64 s[22:23], s[20:21], s[62:63]
	s_add_u32 s4, s22, s2
	s_addc_u32 s5, s23, s3
	s_lshl_b32 s24, s55, 1
	s_ashr_i32 s25, s24, 31
	s_lshl_b64 s[0:1], s[24:25], 2
	s_add_u32 s0, s4, s0
	s_addc_u32 s1, s5, s1
	v_add_u32_e32 v249, s15, v194
	s_add_u32 s20, s0, 0xee3e800
	s_addc_u32 s21, s1, 0
	v_cmp_eq_u32_e64 s[4:5], 0, v249
	s_and_saveexec_b64 s[0:1], s[4:5]
	s_cbranch_execz .LBB0_610
	v_mov_b64_e32 v[194:195], s[20:21]
	flat_atomic_add v194, v[194:195], v237 sc0
	v_readlane_b32 s15, v254, 15
	s_nop 1
	v_mov_b32_e32 v195, s15
	s_waitcnt vmcnt(0) lgkmcnt(0)
	ds_write_b32 v195, v194
	s_waitcnt lgkmcnt(0)
